# hand-written cvt_ffn phase: four 64x64 tiles (32 loads per lane) in flight per workgroup instead of one
# speedup vs baseline: 1.0087x; 1.0085x over previous
; #define LAS __attribute__((address_space(3)))
; __device__ __forceinline__ int otid(int wv0) { int t = (wv0 << 6) | olane(); asm volatile("" : "+v"(t)); return t; }
; __device__ __forceinline__ int obid() { int b = blockIdx.x; asm volatile("" : "+s"(b)); return b; }
; __device__ __forceinline__ int ogrid() { int g = gridDim.x; asm volatile("" : "+s"(g)); return g; }
; __device__ __forceinline__ int rope_src(int j) { return (j & 1) ? 32 + (j >> 1) : (j >> 1); }
; #define CVT_LOAD(t_) do { const int k0_ = ((t_) % nkt) * 64, n0_ = ((t_) / nkt) * 64; const int sn = srcmap(kind, n0_ + nl); \
;     _Pragma("unroll") for (int i = 0; i < 8; ++i) { const int kl = kb + 8 * i; v[i] = 0.f; \
;       if (sn >= 0) { v[i] = src[(size_t)(k0_ + kl) * Nsrc + sn]; if (kscale) v[i] *= kscale[k0_ + kl]; } } } while (0)
; __device__ __forceinline__ int srcmap(int kind, int n) {
;     ...
;   if (kind == 4) { const int pn = n >> 8, lc = n & 255; return lc < 128 ? 128 * pn + lc : DFF + 128 * pn + (lc - 128); }
;   { const int hd = n / 192, c = n % 192; if (c < 128) return n; return hd * 192 + 128 + rope_src(c - 128); }
; }
; __device__ __forceinline__ void cvt_job(LAS unsigned char* lds, const float* src, bf16_t* dst, const float* kscale, int K, int Nsrc, int Ndst, int kind, int wv0, int bid_, int grd_) {
;   LAS float* tile = (LAS float*)lds;
;   const int tid = otid(wv0), nkt = K / 64, ntile = (Ndst / 64) * nkt;
;   if (bid_ < 0) return;
;   const int nl = tid & 63, kb = tid >> 6;
;   float v[8];
;     ...
;   if (bid_ < ntile) CVT_LOAD(bid_);
; __device__ __forceinline__ void cvt_ffn(KP p, int l, LAS unsigned char* lds, int wv0) {
;   unsigned char* W = p->ws; const int f = obid(), st = ogrid();
;   cvt_job(lds, p->w_up + (size_t)l * DM * NUP, (bf16_t*)(W + O_WUP), nullptr, DM, NUP, NUP, 4, wv0, f, st);
.LBB0_1163:
	s_or_b64 exec, exec, s[6:7]
	s_load_dwordx2 s[6:7], s[54:55], 0x98
	s_mul_i32 s2, s66, 0x5800000
	s_mul_hi_u32 s3, s66, 0x5800000
	s_mov_b32 s8, s4
	s_mov_b32 s9, s5
	s_waitcnt lgkmcnt(0)
	s_add_u32 s6, s6, s2
	s_addc_u32 s7, s7, s3
	v_mbcnt_lo_u32_b32 v43, -1, 0
	v_mbcnt_hi_u32_b32 v43, -1, v43
	v_or_b32_e32 v43, s1, v43
	v_and_b32_e32 v44, 63, v43
	v_lshrrev_b32_e32 v40, 6, v43
	s_mov_b32 s10, 0xb000
	v_mul_lo_u32 v32, v40, s10
	v_lshl_add_u32 v32, v44, 2, v32
	v_add_u32_e32 v33, 0x58000, v32
	v_add_u32_e32 v34, 0xb0000, v32
	v_add_u32_e32 v35, 0x108000, v32
	v_add_u32_e32 v36, 0x160000, v32
	v_add_u32_e32 v37, 0x1b8000, v32
	v_add_u32_e32 v38, 0x210000, v32
	v_add_u32_e32 v39, 0x268000, v32
	v_mul_u32_u24_e32 v40, 65, v40
	v_add_lshl_u32 v40, v40, v44, 2
	v_and_b32_e32 v44, 7, v43
	v_lshlrev_b32_e32 v44, 3, v44
	v_lshrrev_b32_e32 v43, 3, v43
	v_mul_u32_u24_e32 v41, 65, v44
	v_add_lshl_u32 v41, v41, v43, 2
	s_movk_i32 s10, 0x800
	v_mul_lo_u32 v42, v43, s10
	v_add_lshl_u32 v42, v42, v44, 1
	s_mov_b32 s11, s82
	s_lshl_b32 s12, s60, 2
	s_mov_b32 s13, 0
	s_add_u32 s13, s13, s11
	s_and_b32 s18, s13, 31
	s_lshr_b32 s19, s13, 5
	s_lshl_b32 s18, s18, 6
	s_lshl_b32 s19, s19, 6
	s_and_b32 s20, s19, 0xff
	s_lshr_b32 s21, s19, 8
	s_lshl_b32 s21, s21, 7
	s_add_u32 s21, s21, s20
	s_add_u32 s22, s21, 0x1580
	s_cmp_lt_u32 s20, 0x80
	s_cselect_b32 s21, s21, s22
	s_mul_i32 s20, s18, 0xb000
	s_lshl_b32 s21, s21, 2
	s_add_u32 s20, s20, s21
	s_add_u32 s14, s6, s20
	s_addc_u32 s15, s7, 0
	s_cmp_lt_u32 s13, 0x1600
	s_cbranch_scc0 .Lcvtup_pl
	global_load_dword v0, v32, s[14:15]
	global_load_dword v1, v33, s[14:15]
	global_load_dword v2, v34, s[14:15]
	global_load_dword v3, v35, s[14:15]
	global_load_dword v4, v36, s[14:15]
	global_load_dword v5, v37, s[14:15]
	global_load_dword v6, v38, s[14:15]
	global_load_dword v7, v39, s[14:15]
	s_mul_i32 s13, s60, 1
	s_add_u32 s13, s13, s11
	s_and_b32 s18, s13, 31
	s_lshr_b32 s19, s13, 5
	s_lshl_b32 s18, s18, 6
	s_lshl_b32 s19, s19, 6
	s_and_b32 s20, s19, 0xff
	s_lshr_b32 s21, s19, 8
	s_lshl_b32 s21, s21, 7
	s_add_u32 s21, s21, s20
	s_add_u32 s22, s21, 0x1580
	s_cmp_lt_u32 s20, 0x80
	s_cselect_b32 s21, s21, s22
	s_mul_i32 s20, s18, 0xb000
	s_lshl_b32 s21, s21, 2
	s_add_u32 s20, s20, s21
	s_add_u32 s14, s6, s20
	s_addc_u32 s15, s7, 0
	s_cmp_lt_u32 s13, 0x1600
	s_cbranch_scc0 .Lcvtup_pl
	global_load_dword v8, v32, s[14:15]
	global_load_dword v9, v33, s[14:15]
	global_load_dword v10, v34, s[14:15]
	global_load_dword v11, v35, s[14:15]
	global_load_dword v12, v36, s[14:15]
	global_load_dword v13, v37, s[14:15]
	global_load_dword v14, v38, s[14:15]
	global_load_dword v15, v39, s[14:15]
	s_mul_i32 s13, s60, 2
	s_add_u32 s13, s13, s11
	s_and_b32 s18, s13, 31
	s_lshr_b32 s19, s13, 5
	s_lshl_b32 s18, s18, 6
	s_lshl_b32 s19, s19, 6
	s_and_b32 s20, s19, 0xff
	s_lshr_b32 s21, s19, 8
	s_lshl_b32 s21, s21, 7
	s_add_u32 s21, s21, s20
	s_add_u32 s22, s21, 0x1580
	s_cmp_lt_u32 s20, 0x80
	s_cselect_b32 s21, s21, s22
	s_mul_i32 s20, s18, 0xb000
	s_lshl_b32 s21, s21, 2
	s_add_u32 s20, s20, s21
	s_add_u32 s14, s6, s20
	s_addc_u32 s15, s7, 0
	s_cmp_lt_u32 s13, 0x1600
	s_cbranch_scc0 .Lcvtup_pl
	global_load_dword v16, v32, s[14:15]
	global_load_dword v17, v33, s[14:15]
	global_load_dword v18, v34, s[14:15]
	global_load_dword v19, v35, s[14:15]
	global_load_dword v20, v36, s[14:15]
	global_load_dword v21, v37, s[14:15]
	global_load_dword v22, v38, s[14:15]
	global_load_dword v23, v39, s[14:15]
	s_mul_i32 s13, s60, 3
	s_add_u32 s13, s13, s11
	s_and_b32 s18, s13, 31
	s_lshr_b32 s19, s13, 5
	s_lshl_b32 s18, s18, 6
	s_lshl_b32 s19, s19, 6
	s_and_b32 s20, s19, 0xff
	s_lshr_b32 s21, s19, 8
	s_lshl_b32 s21, s21, 7
	s_add_u32 s21, s21, s20
	s_add_u32 s22, s21, 0x1580
	s_cmp_lt_u32 s20, 0x80
	s_cselect_b32 s21, s21, s22
	s_mul_i32 s20, s18, 0xb000
	s_lshl_b32 s21, s21, 2
	s_add_u32 s20, s20, s21
	s_add_u32 s14, s6, s20
	s_addc_u32 s15, s7, 0
	s_cmp_lt_u32 s13, 0x1600
	s_cbranch_scc0 .Lcvtup_pl
	global_load_dword v24, v32, s[14:15]
	global_load_dword v25, v33, s[14:15]
	global_load_dword v26, v34, s[14:15]
	global_load_dword v27, v35, s[14:15]
	global_load_dword v28, v36, s[14:15]
	global_load_dword v29, v37, s[14:15]
	global_load_dword v30, v38, s[14:15]
	global_load_dword v31, v39, s[14:15]

; #define CVT_LOAD(t_) do { const int k0_ = ((t_) % nkt) * 64, n0_ = ((t_) / nkt) * 64; const int sn = srcmap(kind, n0_ + nl); \
;     _Pragma("unroll") for (int i = 0; i < 8; ++i) { const int kl = kb + 8 * i; v[i] = 0.f; \
;       if (sn >= 0) { v[i] = src[(size_t)(k0_ + kl) * Nsrc + sn]; if (kscale) v[i] *= kscale[k0_ + kl]; } } } while (0)
; __device__ __forceinline__ void cvt_job(LAS unsigned char* lds, const float* src, bf16_t* dst, const float* kscale, int K, int Nsrc, int Ndst, int kind, int wv0, int bid_, int grd_) {
;     ...
;   for (int t = bid_; t < ntile; t += grd_) {
;     const int k0 = (t % nkt) * 64, n0 = (t / nkt) * 64;
; #pragma unroll
;     for (int i = 0; i < 8; ++i) tile[(kb + 8 * i) * 65 + nl] = v[i];
;     __syncthreads();
;     if (t + grd_ < ntile) CVT_LOAD(t + grd_);
.Lcvtup_loop:
	s_mov_b32 s13, 0
	s_add_u32 s13, s13, s11
	s_cmp_lt_u32 s13, 0x1600
	s_cbranch_scc0 .Lcvtup_wd
	ds_write_b32 v40, v0 offset:0
	ds_write_b32 v40, v1 offset:2080
	ds_write_b32 v40, v2 offset:4160
	ds_write_b32 v40, v3 offset:6240
	ds_write_b32 v40, v4 offset:8320
	ds_write_b32 v40, v5 offset:10400
	ds_write_b32 v40, v6 offset:12480
	ds_write_b32 v40, v7 offset:14560
	s_mul_i32 s13, s60, 1
	s_add_u32 s13, s13, s11
	s_cmp_lt_u32 s13, 0x1600
	s_cbranch_scc0 .Lcvtup_wd
	ds_write_b32 v40, v8 offset:16640
	ds_write_b32 v40, v9 offset:18720
	ds_write_b32 v40, v10 offset:20800
	ds_write_b32 v40, v11 offset:22880
	ds_write_b32 v40, v12 offset:24960
	ds_write_b32 v40, v13 offset:27040
	ds_write_b32 v40, v14 offset:29120
	ds_write_b32 v40, v15 offset:31200
	s_mul_i32 s13, s60, 2
	s_add_u32 s13, s13, s11
	s_cmp_lt_u32 s13, 0x1600
	s_cbranch_scc0 .Lcvtup_wd
	ds_write_b32 v40, v16 offset:33280
	ds_write_b32 v40, v17 offset:35360
	ds_write_b32 v40, v18 offset:37440
	ds_write_b32 v40, v19 offset:39520
	ds_write_b32 v40, v20 offset:41600
	ds_write_b32 v40, v21 offset:43680
	ds_write_b32 v40, v22 offset:45760
	ds_write_b32 v40, v23 offset:47840
	s_mul_i32 s13, s60, 3
	s_add_u32 s13, s13, s11
	s_cmp_lt_u32 s13, 0x1600
	s_cbranch_scc0 .Lcvtup_wd
	ds_write_b32 v40, v24 offset:49920
	ds_write_b32 v40, v25 offset:52000
	ds_write_b32 v40, v26 offset:54080
	ds_write_b32 v40, v27 offset:56160
	ds_write_b32 v40, v28 offset:58240
	ds_write_b32 v40, v29 offset:60320
	ds_write_b32 v40, v30 offset:62400
	ds_write_b32 v40, v31 offset:64480
.Lcvtup_wd:
	s_waitcnt lgkmcnt(0)
	s_barrier
	s_add_u32 s11, s11, s12
	s_mov_b32 s13, 0
	s_add_u32 s13, s13, s11
	s_and_b32 s18, s13, 31
	s_lshr_b32 s19, s13, 5
	s_lshl_b32 s18, s18, 6
	s_lshl_b32 s19, s19, 6
	s_and_b32 s20, s19, 0xff
	s_lshr_b32 s21, s19, 8
	s_lshl_b32 s21, s21, 7
	s_add_u32 s21, s21, s20
	s_add_u32 s22, s21, 0x1580
	s_cmp_lt_u32 s20, 0x80
	s_cselect_b32 s21, s21, s22
	s_mul_i32 s20, s18, 0xb000
	s_lshl_b32 s21, s21, 2
	s_add_u32 s20, s20, s21
	s_add_u32 s14, s6, s20
	s_addc_u32 s15, s7, 0
	s_cmp_lt_u32 s13, 0x1600
	s_cbranch_scc0 .Lcvtup_nl
	global_load_dword v0, v32, s[14:15]
	global_load_dword v1, v33, s[14:15]
	global_load_dword v2, v34, s[14:15]
	global_load_dword v3, v35, s[14:15]
	global_load_dword v4, v36, s[14:15]
	global_load_dword v5, v37, s[14:15]
	global_load_dword v6, v38, s[14:15]
	global_load_dword v7, v39, s[14:15]
	s_mul_i32 s13, s60, 1
	s_add_u32 s13, s13, s11
	s_and_b32 s18, s13, 31
	s_lshr_b32 s19, s13, 5
	s_lshl_b32 s18, s18, 6
	s_lshl_b32 s19, s19, 6
	s_and_b32 s20, s19, 0xff
	s_lshr_b32 s21, s19, 8
	s_lshl_b32 s21, s21, 7
	s_add_u32 s21, s21, s20
	s_add_u32 s22, s21, 0x1580
	s_cmp_lt_u32 s20, 0x80
	s_cselect_b32 s21, s21, s22
	s_mul_i32 s20, s18, 0xb000
	s_lshl_b32 s21, s21, 2
	s_add_u32 s20, s20, s21
	s_add_u32 s14, s6, s20
	s_addc_u32 s15, s7, 0
	s_cmp_lt_u32 s13, 0x1600
	s_cbranch_scc0 .Lcvtup_nl
	global_load_dword v8, v32, s[14:15]
	global_load_dword v9, v33, s[14:15]
	global_load_dword v10, v34, s[14:15]
	global_load_dword v11, v35, s[14:15]
	global_load_dword v12, v36, s[14:15]
	global_load_dword v13, v37, s[14:15]
	global_load_dword v14, v38, s[14:15]
	global_load_dword v15, v39, s[14:15]
	s_mul_i32 s13, s60, 2
	s_add_u32 s13, s13, s11
	s_and_b32 s18, s13, 31
	s_lshr_b32 s19, s13, 5
	s_lshl_b32 s18, s18, 6
	s_lshl_b32 s19, s19, 6
	s_and_b32 s20, s19, 0xff
	s_lshr_b32 s21, s19, 8
	s_lshl_b32 s21, s21, 7
	s_add_u32 s21, s21, s20
	s_add_u32 s22, s21, 0x1580
	s_cmp_lt_u32 s20, 0x80
	s_cselect_b32 s21, s21, s22
	s_mul_i32 s20, s18, 0xb000
	s_lshl_b32 s21, s21, 2
	s_add_u32 s20, s20, s21
	s_add_u32 s14, s6, s20
	s_addc_u32 s15, s7, 0
	s_cmp_lt_u32 s13, 0x1600
	s_cbranch_scc0 .Lcvtup_nl
	global_load_dword v16, v32, s[14:15]
	global_load_dword v17, v33, s[14:15]
	global_load_dword v18, v34, s[14:15]
	global_load_dword v19, v35, s[14:15]
	global_load_dword v20, v36, s[14:15]
	global_load_dword v21, v37, s[14:15]
	global_load_dword v22, v38, s[14:15]
	global_load_dword v23, v39, s[14:15]
	s_mul_i32 s13, s60, 3
	s_add_u32 s13, s13, s11
	s_and_b32 s18, s13, 31
	s_lshr_b32 s19, s13, 5
	s_lshl_b32 s18, s18, 6
	s_lshl_b32 s19, s19, 6
	s_and_b32 s20, s19, 0xff
	s_lshr_b32 s21, s19, 8
	s_lshl_b32 s21, s21, 7
	s_add_u32 s21, s21, s20
	s_add_u32 s22, s21, 0x1580
	s_cmp_lt_u32 s20, 0x80
	s_cselect_b32 s21, s21, s22
	s_mul_i32 s20, s18, 0xb000
	s_lshl_b32 s21, s21, 2
	s_add_u32 s20, s20, s21
	s_add_u32 s14, s6, s20
	s_addc_u32 s15, s7, 0
	s_cmp_lt_u32 s13, 0x1600
	s_cbranch_scc0 .Lcvtup_nl
	global_load_dword v24, v32, s[14:15]
	global_load_dword v25, v33, s[14:15]
	global_load_dword v26, v34, s[14:15]
	global_load_dword v27, v35, s[14:15]
	global_load_dword v28, v36, s[14:15]
	global_load_dword v29, v37, s[14:15]
	global_load_dword v30, v38, s[14:15]
	global_load_dword v31, v39, s[14:15]
; __device__ __forceinline__ void cvt_job(LAS unsigned char* lds, const float* src, bf16_t* dst, const float* kscale, int K, int Nsrc, int Ndst, int kind, int wv0, int bid_, int grd_) {
;     ...
;     { const int nl2 = tid >> 3, kc = (tid & 7) * 8; float w[8];
; #pragma unroll
;       for (int j = 0; j < 8; ++j) w[j] = tile[(kc + j) * 65 + nl2];
;       store8bf(dst + (size_t)(n0 + nl2) * K + k0 + kc, w); }
;     __syncthreads();
;   }
.Lcvtup_nl:
	s_sub_u32 s11, s11, s12
	s_mov_b32 s13, 0
	s_add_u32 s13, s13, s11
	s_and_b32 s18, s13, 31
	s_lshr_b32 s19, s13, 5
	s_lshl_b32 s18, s18, 6
	s_lshl_b32 s19, s19, 6
	s_mul_i32 s20, s19, 0x800
	s_add_u32 s20, s20, s18
	s_lshl_b32 s20, s20, 1
	s_add_u32 s16, s8, s20
	s_addc_u32 s17, s9, 0
	s_cmp_lt_u32 s13, 0x1600
	s_cbranch_scc0 .Lcvtup_sd
	ds_read_b32 v98, v41 offset:0
	ds_read_b32 v99, v41 offset:260
	ds_read_b32 v100, v41 offset:520
	ds_read_b32 v101, v41 offset:780
	ds_read_b32 v102, v41 offset:1040
	ds_read_b32 v103, v41 offset:1300
	ds_read_b32 v104, v41 offset:1560
	ds_read_b32 v105, v41 offset:1820
	s_waitcnt lgkmcnt(0)
	v_cvt_pk_bf16_f32 v130, v98, v99
	v_cvt_pk_bf16_f32 v131, v100, v101
	v_cvt_pk_bf16_f32 v132, v102, v103
	v_cvt_pk_bf16_f32 v133, v104, v105
	global_store_dwordx4 v42, v[130:133], s[16:17]
	s_mul_i32 s13, s60, 1
	s_add_u32 s13, s13, s11
	s_and_b32 s18, s13, 31
	s_lshr_b32 s19, s13, 5
	s_lshl_b32 s18, s18, 6
	s_lshl_b32 s19, s19, 6
	s_mul_i32 s20, s19, 0x800
	s_add_u32 s20, s20, s18
	s_lshl_b32 s20, s20, 1
	s_add_u32 s16, s8, s20
	s_addc_u32 s17, s9, 0
	s_cmp_lt_u32 s13, 0x1600
	s_cbranch_scc0 .Lcvtup_sd
	ds_read_b32 v106, v41 offset:16640
	ds_read_b32 v107, v41 offset:16900
	ds_read_b32 v108, v41 offset:17160
	ds_read_b32 v109, v41 offset:17420
	ds_read_b32 v110, v41 offset:17680
	ds_read_b32 v111, v41 offset:17940
	ds_read_b32 v112, v41 offset:18200
	ds_read_b32 v113, v41 offset:18460
	s_waitcnt lgkmcnt(0)
	v_cvt_pk_bf16_f32 v134, v106, v107
	v_cvt_pk_bf16_f32 v135, v108, v109
	v_cvt_pk_bf16_f32 v136, v110, v111
	v_cvt_pk_bf16_f32 v137, v112, v113
	global_store_dwordx4 v42, v[134:137], s[16:17]
	s_mul_i32 s13, s60, 2
	s_add_u32 s13, s13, s11
	s_and_b32 s18, s13, 31
	s_lshr_b32 s19, s13, 5
	s_lshl_b32 s18, s18, 6
	s_lshl_b32 s19, s19, 6
	s_mul_i32 s20, s19, 0x800
	s_add_u32 s20, s20, s18
	s_lshl_b32 s20, s20, 1
	s_add_u32 s16, s8, s20
	s_addc_u32 s17, s9, 0
	s_cmp_lt_u32 s13, 0x1600
	s_cbranch_scc0 .Lcvtup_sd
	ds_read_b32 v114, v41 offset:33280
	ds_read_b32 v115, v41 offset:33540
	ds_read_b32 v116, v41 offset:33800
	ds_read_b32 v117, v41 offset:34060
	ds_read_b32 v118, v41 offset:34320
	ds_read_b32 v119, v41 offset:34580
	ds_read_b32 v120, v41 offset:34840
	ds_read_b32 v121, v41 offset:35100
	s_waitcnt lgkmcnt(0)
	v_cvt_pk_bf16_f32 v138, v114, v115
	v_cvt_pk_bf16_f32 v139, v116, v117
	v_cvt_pk_bf16_f32 v140, v118, v119
	v_cvt_pk_bf16_f32 v141, v120, v121
	global_store_dwordx4 v42, v[138:141], s[16:17]
	s_mul_i32 s13, s60, 3
	s_add_u32 s13, s13, s11
	s_and_b32 s18, s13, 31
	s_lshr_b32 s19, s13, 5
	s_lshl_b32 s18, s18, 6
	s_lshl_b32 s19, s19, 6
	s_mul_i32 s20, s19, 0x800
	s_add_u32 s20, s20, s18
	s_lshl_b32 s20, s20, 1
	s_add_u32 s16, s8, s20
	s_addc_u32 s17, s9, 0
	s_cmp_lt_u32 s13, 0x1600
	s_cbranch_scc0 .Lcvtup_sd
	ds_read_b32 v122, v41 offset:49920
	ds_read_b32 v123, v41 offset:50180
	ds_read_b32 v124, v41 offset:50440
	ds_read_b32 v125, v41 offset:50700
	ds_read_b32 v126, v41 offset:50960
	ds_read_b32 v127, v41 offset:51220
	ds_read_b32 v128, v41 offset:51480
	ds_read_b32 v129, v41 offset:51740
	s_waitcnt lgkmcnt(0)
	v_cvt_pk_bf16_f32 v142, v122, v123
	v_cvt_pk_bf16_f32 v143, v124, v125
	v_cvt_pk_bf16_f32 v144, v126, v127
	v_cvt_pk_bf16_f32 v145, v128, v129
	global_store_dwordx4 v42, v[142:145], s[16:17]
.Lcvtup_sd:
	s_barrier
	s_add_u32 s11, s11, s12
	s_cmp_lt_u32 s11, 0x1600
	s_cbranch_scc0 .Lcvtup_end
	s_waitcnt vmcnt(4)
	s_branch .Lcvtup_loop
; #define LAS __attribute__((address_space(3)))
; __device__ __forceinline__ int otid(int wv0) { int t = (wv0 << 6) | olane(); asm volatile("" : "+v"(t)); return t; }
; __device__ __forceinline__ int obid() { int b = blockIdx.x; asm volatile("" : "+s"(b)); return b; }
; __device__ __forceinline__ int ogrid() { int g = gridDim.x; asm volatile("" : "+s"(g)); return g; }
; #define CVT_LOAD(t_) do { const int k0_ = ((t_) % nkt) * 64, n0_ = ((t_) / nkt) * 64; const int sn = srcmap(kind, n0_ + nl); \
;     _Pragma("unroll") for (int i = 0; i < 8; ++i) { const int kl = kb + 8 * i; v[i] = 0.f; \
;       if (sn >= 0) { v[i] = src[(size_t)(k0_ + kl) * Nsrc + sn]; if (kscale) v[i] *= kscale[k0_ + kl]; } } } while (0)
; __device__ __forceinline__ void cvt_job(LAS unsigned char* lds, const float* src, bf16_t* dst, const float* kscale, int K, int Nsrc, int Ndst, int kind, int wv0, int bid_, int grd_) {
;   LAS float* tile = (LAS float*)lds;
;   const int tid = otid(wv0), nkt = K / 64, ntile = (Ndst / 64) * nkt;
;   if (bid_ < 0) return;
;   const int nl = tid & 63, kb = tid >> 6;
;   float v[8];
;     ...
;   if (bid_ < ntile) CVT_LOAD(bid_);
; __device__ __forceinline__ void cvt_ffn(KP p, int l, LAS unsigned char* lds, int wv0) {
;   unsigned char* W = p->ws; const int f = obid(), st = ogrid();
;   cvt_job(lds, p->w_up + (size_t)l * DM * NUP, (bf16_t*)(W + O_WUP), nullptr, DM, NUP, NUP, 4, wv0, f, st);
;   cvt_job(lds, p->w_down + (size_t)l * DFF * DM, (bf16_t*)(W + O_WDN), nullptr, DFF, DM, DM, 0, wv0, f, st);
.Lcvtup_end:
	s_waitcnt vmcnt(0)
	s_load_dwordx2 s[6:7], s[54:55], 0xb0
	s_mul_i32 s2, s66, 0x2c00000
	s_mul_hi_u32 s3, s66, 0x2c00000
	s_add_u32 s8, s4, 0x2c00000
	s_addc_u32 s9, s5, 0
	s_waitcnt lgkmcnt(0)
	s_add_u32 s6, s6, s2
	s_addc_u32 s7, s7, s3
	v_mbcnt_lo_u32_b32 v43, -1, 0
	v_mbcnt_hi_u32_b32 v43, -1, v43
	v_or_b32_e32 v43, s1, v43
	v_and_b32_e32 v44, 63, v43
	v_lshrrev_b32_e32 v40, 6, v43
	s_mov_b32 s10, 0x2000
	v_mul_lo_u32 v32, v40, s10
	v_lshl_add_u32 v32, v44, 2, v32
	v_add_u32_e32 v33, 0x10000, v32
	v_add_u32_e32 v34, 0x20000, v32
	v_add_u32_e32 v35, 0x30000, v32
	v_add_u32_e32 v36, 0x40000, v32
	v_add_u32_e32 v37, 0x50000, v32
	v_add_u32_e32 v38, 0x60000, v32
	v_add_u32_e32 v39, 0x70000, v32
	v_mul_u32_u24_e32 v40, 65, v40
	v_add_lshl_u32 v40, v40, v44, 2
	v_and_b32_e32 v44, 7, v43
	v_lshlrev_b32_e32 v44, 3, v44
	v_lshrrev_b32_e32 v43, 3, v43
	v_mul_u32_u24_e32 v41, 65, v44
	v_add_lshl_u32 v41, v41, v43, 2
	s_movk_i32 s10, 0x1600
	v_mul_lo_u32 v42, v43, s10
	v_add_lshl_u32 v42, v42, v44, 1
	s_mov_b32 s11, s82
	s_lshl_b32 s12, s60, 2
	s_mov_b32 s13, 0
	s_add_u32 s13, s13, s11
	s_mul_i32 s19, s13, 0xba2f
	s_lshr_b32 s19, s19, 22
	s_mul_i32 s18, s19, 88
	s_sub_u32 s18, s13, s18
	s_lshl_b32 s18, s18, 6
	s_lshl_b32 s19, s19, 6
	s_mov_b32 s21, s19
	s_mul_i32 s20, s18, 0x2000
	s_lshl_b32 s21, s21, 2
	s_add_u32 s20, s20, s21
	s_add_u32 s14, s6, s20
	s_addc_u32 s15, s7, 0
	s_cmp_lt_u32 s13, 0xb00
	s_cbranch_scc0 .Lcvtdn_pl
	global_load_dword v0, v32, s[14:15]
	global_load_dword v1, v33, s[14:15]
	global_load_dword v2, v34, s[14:15]
	global_load_dword v3, v35, s[14:15]
	global_load_dword v4, v36, s[14:15]
	global_load_dword v5, v37, s[14:15]
	global_load_dword v6, v38, s[14:15]
	global_load_dword v7, v39, s[14:15]
	s_mul_i32 s13, s60, 1
	s_add_u32 s13, s13, s11
	s_mul_i32 s19, s13, 0xba2f
	s_lshr_b32 s19, s19, 22
	s_mul_i32 s18, s19, 88
	s_sub_u32 s18, s13, s18
	s_lshl_b32 s18, s18, 6
	s_lshl_b32 s19, s19, 6
	s_mov_b32 s21, s19
	s_mul_i32 s20, s18, 0x2000
	s_lshl_b32 s21, s21, 2
	s_add_u32 s20, s20, s21
	s_add_u32 s14, s6, s20
	s_addc_u32 s15, s7, 0
	s_cmp_lt_u32 s13, 0xb00
	s_cbranch_scc0 .Lcvtdn_pl
	global_load_dword v8, v32, s[14:15]
	global_load_dword v9, v33, s[14:15]
	global_load_dword v10, v34, s[14:15]
	global_load_dword v11, v35, s[14:15]
	global_load_dword v12, v36, s[14:15]
	global_load_dword v13, v37, s[14:15]
	global_load_dword v14, v38, s[14:15]
	global_load_dword v15, v39, s[14:15]
	s_mul_i32 s13, s60, 2
	s_add_u32 s13, s13, s11
	s_mul_i32 s19, s13, 0xba2f
	s_lshr_b32 s19, s19, 22
	s_mul_i32 s18, s19, 88
	s_sub_u32 s18, s13, s18
	s_lshl_b32 s18, s18, 6
	s_lshl_b32 s19, s19, 6
	s_mov_b32 s21, s19
	s_mul_i32 s20, s18, 0x2000
	s_lshl_b32 s21, s21, 2
	s_add_u32 s20, s20, s21
	s_add_u32 s14, s6, s20
	s_addc_u32 s15, s7, 0
	s_cmp_lt_u32 s13, 0xb00
	s_cbranch_scc0 .Lcvtdn_pl
	global_load_dword v16, v32, s[14:15]
	global_load_dword v17, v33, s[14:15]
	global_load_dword v18, v34, s[14:15]
	global_load_dword v19, v35, s[14:15]
	global_load_dword v20, v36, s[14:15]
	global_load_dword v21, v37, s[14:15]
	global_load_dword v22, v38, s[14:15]
	global_load_dword v23, v39, s[14:15]
	s_mul_i32 s13, s60, 3
	s_add_u32 s13, s13, s11
	s_mul_i32 s19, s13, 0xba2f
	s_lshr_b32 s19, s19, 22
	s_mul_i32 s18, s19, 88
	s_sub_u32 s18, s13, s18
	s_lshl_b32 s18, s18, 6
	s_lshl_b32 s19, s19, 6
	s_mov_b32 s21, s19
	s_mul_i32 s20, s18, 0x2000
	s_lshl_b32 s21, s21, 2
	s_add_u32 s20, s20, s21
	s_add_u32 s14, s6, s20
	s_addc_u32 s15, s7, 0
	s_cmp_lt_u32 s13, 0xb00
	s_cbranch_scc0 .Lcvtdn_pl
	global_load_dword v24, v32, s[14:15]
	global_load_dword v25, v33, s[14:15]
	global_load_dword v26, v34, s[14:15]
	global_load_dword v27, v35, s[14:15]
	global_load_dword v28, v36, s[14:15]
	global_load_dword v29, v37, s[14:15]
	global_load_dword v30, v38, s[14:15]
	global_load_dword v31, v39, s[14:15]

; #define CVT_LOAD(t_) do { const int k0_ = ((t_) % nkt) * 64, n0_ = ((t_) / nkt) * 64; const int sn = srcmap(kind, n0_ + nl); \
;     _Pragma("unroll") for (int i = 0; i < 8; ++i) { const int kl = kb + 8 * i; v[i] = 0.f; \
;       if (sn >= 0) { v[i] = src[(size_t)(k0_ + kl) * Nsrc + sn]; if (kscale) v[i] *= kscale[k0_ + kl]; } } } while (0)
; __device__ __forceinline__ void cvt_job(LAS unsigned char* lds, const float* src, bf16_t* dst, const float* kscale, int K, int Nsrc, int Ndst, int kind, int wv0, int bid_, int grd_) {
;     ...
;   for (int t = bid_; t < ntile; t += grd_) {
;     const int k0 = (t % nkt) * 64, n0 = (t / nkt) * 64;
; #pragma unroll
;     for (int i = 0; i < 8; ++i) tile[(kb + 8 * i) * 65 + nl] = v[i];
;     __syncthreads();
;     if (t + grd_ < ntile) CVT_LOAD(t + grd_);
.Lcvtdn_loop:
	s_mov_b32 s13, 0
	s_add_u32 s13, s13, s11
	s_cmp_lt_u32 s13, 0xb00
	s_cbranch_scc0 .Lcvtdn_wd
	ds_write_b32 v40, v0 offset:0
	ds_write_b32 v40, v1 offset:2080
	ds_write_b32 v40, v2 offset:4160
	ds_write_b32 v40, v3 offset:6240
	ds_write_b32 v40, v4 offset:8320
	ds_write_b32 v40, v5 offset:10400
	ds_write_b32 v40, v6 offset:12480
	ds_write_b32 v40, v7 offset:14560
	s_mul_i32 s13, s60, 1
	s_add_u32 s13, s13, s11
	s_cmp_lt_u32 s13, 0xb00
	s_cbranch_scc0 .Lcvtdn_wd
	ds_write_b32 v40, v8 offset:16640
	ds_write_b32 v40, v9 offset:18720
	ds_write_b32 v40, v10 offset:20800
	ds_write_b32 v40, v11 offset:22880
	ds_write_b32 v40, v12 offset:24960
	ds_write_b32 v40, v13 offset:27040
	ds_write_b32 v40, v14 offset:29120
	ds_write_b32 v40, v15 offset:31200
	s_mul_i32 s13, s60, 2
	s_add_u32 s13, s13, s11
	s_cmp_lt_u32 s13, 0xb00
	s_cbranch_scc0 .Lcvtdn_wd
	ds_write_b32 v40, v16 offset:33280
	ds_write_b32 v40, v17 offset:35360
	ds_write_b32 v40, v18 offset:37440
	ds_write_b32 v40, v19 offset:39520
	ds_write_b32 v40, v20 offset:41600
	ds_write_b32 v40, v21 offset:43680
	ds_write_b32 v40, v22 offset:45760
	ds_write_b32 v40, v23 offset:47840
	s_mul_i32 s13, s60, 3
	s_add_u32 s13, s13, s11
	s_cmp_lt_u32 s13, 0xb00
	s_cbranch_scc0 .Lcvtdn_wd
	ds_write_b32 v40, v24 offset:49920
	ds_write_b32 v40, v25 offset:52000
	ds_write_b32 v40, v26 offset:54080
	ds_write_b32 v40, v27 offset:56160
	ds_write_b32 v40, v28 offset:58240
	ds_write_b32 v40, v29 offset:60320
	ds_write_b32 v40, v30 offset:62400
	ds_write_b32 v40, v31 offset:64480
.Lcvtdn_wd:
	s_waitcnt lgkmcnt(0)
	s_barrier
	s_add_u32 s11, s11, s12
	s_mov_b32 s13, 0
	s_add_u32 s13, s13, s11
	s_mul_i32 s19, s13, 0xba2f
	s_lshr_b32 s19, s19, 22
	s_mul_i32 s18, s19, 88
	s_sub_u32 s18, s13, s18
	s_lshl_b32 s18, s18, 6
	s_lshl_b32 s19, s19, 6
	s_mov_b32 s21, s19
	s_mul_i32 s20, s18, 0x2000
	s_lshl_b32 s21, s21, 2
	s_add_u32 s20, s20, s21
	s_add_u32 s14, s6, s20
	s_addc_u32 s15, s7, 0
	s_cmp_lt_u32 s13, 0xb00
	s_cbranch_scc0 .Lcvtdn_nl
	global_load_dword v0, v32, s[14:15]
	global_load_dword v1, v33, s[14:15]
	global_load_dword v2, v34, s[14:15]
	global_load_dword v3, v35, s[14:15]
	global_load_dword v4, v36, s[14:15]
	global_load_dword v5, v37, s[14:15]
	global_load_dword v6, v38, s[14:15]
	global_load_dword v7, v39, s[14:15]
	s_mul_i32 s13, s60, 1
	s_add_u32 s13, s13, s11
	s_mul_i32 s19, s13, 0xba2f
	s_lshr_b32 s19, s19, 22
	s_mul_i32 s18, s19, 88
	s_sub_u32 s18, s13, s18
	s_lshl_b32 s18, s18, 6
	s_lshl_b32 s19, s19, 6
	s_mov_b32 s21, s19
	s_mul_i32 s20, s18, 0x2000
	s_lshl_b32 s21, s21, 2
	s_add_u32 s20, s20, s21
	s_add_u32 s14, s6, s20
	s_addc_u32 s15, s7, 0
	s_cmp_lt_u32 s13, 0xb00
	s_cbranch_scc0 .Lcvtdn_nl
	global_load_dword v8, v32, s[14:15]
	global_load_dword v9, v33, s[14:15]
	global_load_dword v10, v34, s[14:15]
	global_load_dword v11, v35, s[14:15]
	global_load_dword v12, v36, s[14:15]
	global_load_dword v13, v37, s[14:15]
	global_load_dword v14, v38, s[14:15]
	global_load_dword v15, v39, s[14:15]
	s_mul_i32 s13, s60, 2
	s_add_u32 s13, s13, s11
	s_mul_i32 s19, s13, 0xba2f
	s_lshr_b32 s19, s19, 22
	s_mul_i32 s18, s19, 88
	s_sub_u32 s18, s13, s18
	s_lshl_b32 s18, s18, 6
	s_lshl_b32 s19, s19, 6
	s_mov_b32 s21, s19
	s_mul_i32 s20, s18, 0x2000
	s_lshl_b32 s21, s21, 2
	s_add_u32 s20, s20, s21
	s_add_u32 s14, s6, s20
	s_addc_u32 s15, s7, 0
	s_cmp_lt_u32 s13, 0xb00
	s_cbranch_scc0 .Lcvtdn_nl
	global_load_dword v16, v32, s[14:15]
	global_load_dword v17, v33, s[14:15]
	global_load_dword v18, v34, s[14:15]
	global_load_dword v19, v35, s[14:15]
	global_load_dword v20, v36, s[14:15]
	global_load_dword v21, v37, s[14:15]
	global_load_dword v22, v38, s[14:15]
	global_load_dword v23, v39, s[14:15]
	s_mul_i32 s13, s60, 3
	s_add_u32 s13, s13, s11
	s_mul_i32 s19, s13, 0xba2f
	s_lshr_b32 s19, s19, 22
	s_mul_i32 s18, s19, 88
	s_sub_u32 s18, s13, s18
	s_lshl_b32 s18, s18, 6
	s_lshl_b32 s19, s19, 6
	s_mov_b32 s21, s19
	s_mul_i32 s20, s18, 0x2000
	s_lshl_b32 s21, s21, 2
	s_add_u32 s20, s20, s21
	s_add_u32 s14, s6, s20
	s_addc_u32 s15, s7, 0
	s_cmp_lt_u32 s13, 0xb00
	s_cbranch_scc0 .Lcvtdn_nl
	global_load_dword v24, v32, s[14:15]
	global_load_dword v25, v33, s[14:15]
	global_load_dword v26, v34, s[14:15]
	global_load_dword v27, v35, s[14:15]
	global_load_dword v28, v36, s[14:15]
	global_load_dword v29, v37, s[14:15]
	global_load_dword v30, v38, s[14:15]
	global_load_dword v31, v39, s[14:15]
; #define LAS __attribute__((address_space(3)))
; __device__ __forceinline__ int otid(int wv0) { int t = (wv0 << 6) | olane(); asm volatile("" : "+v"(t)); return t; }
; __device__ __forceinline__ unsigned xb_add(unsigned* p, unsigned v) { return __hip_atomic_fetch_add(p, v, __ATOMIC_RELAXED, __HIP_MEMORY_SCOPE_AGENT); }
; __device__ __forceinline__ unsigned xb_xcc_id() { return (unsigned)__builtin_amdgcn_s_getreg((3 << 11) | 20) & 0xFu; }
; __device__ __forceinline__ void cvt_job(LAS unsigned char* lds, const float* src, bf16_t* dst, const float* kscale, int K, int Nsrc, int Ndst, int kind, int wv0, int bid_, int grd_) {
;     ...
;     { const int nl2 = tid >> 3, kc = (tid & 7) * 8; float w[8];
; #pragma unroll
;       for (int j = 0; j < 8; ++j) w[j] = tile[(kc + j) * 65 + nl2];
;       store8bf(dst + (size_t)(n0 + nl2) * K + k0 + kc, w); }
;     __syncthreads();
;   }
; __device__ __forceinline__ void xcd_barrier(unsigned* bar, volatile LAS unsigned* st, int wv0) {
;     asm volatile("s_waitcnt vmcnt(0)" ::: "memory");
;     __syncthreads();
;     if (otid(wv0) == 0) {
;         const unsigned x = xb_xcc_id();
;         __builtin_amdgcn_s_waitcnt(0);
;         unsigned nloc = st[0], nx = st[1];
;         if (nloc == 0u) { xcd_barrier_complete(bar, x, nloc, nx); st[0] = nloc; st[1] = nx; }
;         const unsigned old = xb_add(&bar[XB_XSUB(x)], 1u);
.Lcvtdn_nl:
	s_sub_u32 s11, s11, s12
	s_mov_b32 s13, 0
	s_add_u32 s13, s13, s11
	s_mul_i32 s19, s13, 0xba2f
	s_lshr_b32 s19, s19, 22
	s_mul_i32 s18, s19, 88
	s_sub_u32 s18, s13, s18
	s_lshl_b32 s18, s18, 6
	s_lshl_b32 s19, s19, 6
	s_mul_i32 s20, s19, 0x1600
	s_add_u32 s20, s20, s18
	s_lshl_b32 s20, s20, 1
	s_add_u32 s16, s8, s20
	s_addc_u32 s17, s9, 0
	s_cmp_lt_u32 s13, 0xb00
	s_cbranch_scc0 .Lcvtdn_sd
	ds_read_b32 v98, v41 offset:0
	ds_read_b32 v99, v41 offset:260
	ds_read_b32 v100, v41 offset:520
	ds_read_b32 v101, v41 offset:780
	ds_read_b32 v102, v41 offset:1040
	ds_read_b32 v103, v41 offset:1300
	ds_read_b32 v104, v41 offset:1560
	ds_read_b32 v105, v41 offset:1820
	s_waitcnt lgkmcnt(0)
	v_cvt_pk_bf16_f32 v130, v98, v99
	v_cvt_pk_bf16_f32 v131, v100, v101
	v_cvt_pk_bf16_f32 v132, v102, v103
	v_cvt_pk_bf16_f32 v133, v104, v105
	global_store_dwordx4 v42, v[130:133], s[16:17]
	s_mul_i32 s13, s60, 1
	s_add_u32 s13, s13, s11
	s_mul_i32 s19, s13, 0xba2f
	s_lshr_b32 s19, s19, 22
	s_mul_i32 s18, s19, 88
	s_sub_u32 s18, s13, s18
	s_lshl_b32 s18, s18, 6
	s_lshl_b32 s19, s19, 6
	s_mul_i32 s20, s19, 0x1600
	s_add_u32 s20, s20, s18
	s_lshl_b32 s20, s20, 1
	s_add_u32 s16, s8, s20
	s_addc_u32 s17, s9, 0
	s_cmp_lt_u32 s13, 0xb00
	s_cbranch_scc0 .Lcvtdn_sd
	ds_read_b32 v106, v41 offset:16640
	ds_read_b32 v107, v41 offset:16900
	ds_read_b32 v108, v41 offset:17160
	ds_read_b32 v109, v41 offset:17420
	ds_read_b32 v110, v41 offset:17680
	ds_read_b32 v111, v41 offset:17940
	ds_read_b32 v112, v41 offset:18200
	ds_read_b32 v113, v41 offset:18460
	s_waitcnt lgkmcnt(0)
	v_cvt_pk_bf16_f32 v134, v106, v107
	v_cvt_pk_bf16_f32 v135, v108, v109
	v_cvt_pk_bf16_f32 v136, v110, v111
	v_cvt_pk_bf16_f32 v137, v112, v113
	global_store_dwordx4 v42, v[134:137], s[16:17]
	s_mul_i32 s13, s60, 2
	s_add_u32 s13, s13, s11
	s_mul_i32 s19, s13, 0xba2f
	s_lshr_b32 s19, s19, 22
	s_mul_i32 s18, s19, 88
	s_sub_u32 s18, s13, s18
	s_lshl_b32 s18, s18, 6
	s_lshl_b32 s19, s19, 6
	s_mul_i32 s20, s19, 0x1600
	s_add_u32 s20, s20, s18
	s_lshl_b32 s20, s20, 1
	s_add_u32 s16, s8, s20
	s_addc_u32 s17, s9, 0
	s_cmp_lt_u32 s13, 0xb00
	s_cbranch_scc0 .Lcvtdn_sd
	ds_read_b32 v114, v41 offset:33280
	ds_read_b32 v115, v41 offset:33540
	ds_read_b32 v116, v41 offset:33800
	ds_read_b32 v117, v41 offset:34060
	ds_read_b32 v118, v41 offset:34320
	ds_read_b32 v119, v41 offset:34580
	ds_read_b32 v120, v41 offset:34840
	ds_read_b32 v121, v41 offset:35100
	s_waitcnt lgkmcnt(0)
	v_cvt_pk_bf16_f32 v138, v114, v115
	v_cvt_pk_bf16_f32 v139, v116, v117
	v_cvt_pk_bf16_f32 v140, v118, v119
	v_cvt_pk_bf16_f32 v141, v120, v121
	global_store_dwordx4 v42, v[138:141], s[16:17]
	s_mul_i32 s13, s60, 3
	s_add_u32 s13, s13, s11
	s_mul_i32 s19, s13, 0xba2f
	s_lshr_b32 s19, s19, 22
	s_mul_i32 s18, s19, 88
	s_sub_u32 s18, s13, s18
	s_lshl_b32 s18, s18, 6
	s_lshl_b32 s19, s19, 6
	s_mul_i32 s20, s19, 0x1600
	s_add_u32 s20, s20, s18
	s_lshl_b32 s20, s20, 1
	s_add_u32 s16, s8, s20
	s_addc_u32 s17, s9, 0
	s_cmp_lt_u32 s13, 0xb00
	s_cbranch_scc0 .Lcvtdn_sd
	ds_read_b32 v122, v41 offset:49920
	ds_read_b32 v123, v41 offset:50180
	ds_read_b32 v124, v41 offset:50440
	ds_read_b32 v125, v41 offset:50700
	ds_read_b32 v126, v41 offset:50960
	ds_read_b32 v127, v41 offset:51220
	ds_read_b32 v128, v41 offset:51480
	ds_read_b32 v129, v41 offset:51740
	s_waitcnt lgkmcnt(0)
	v_cvt_pk_bf16_f32 v142, v122, v123
	v_cvt_pk_bf16_f32 v143, v124, v125
	v_cvt_pk_bf16_f32 v144, v126, v127
	v_cvt_pk_bf16_f32 v145, v128, v129
	global_store_dwordx4 v42, v[142:145], s[16:17]
.Lcvtdn_sd:
	s_barrier
	s_add_u32 s11, s11, s12
	s_cmp_lt_u32 s11, 0xb00
	s_cbranch_scc0 .Lcvtdn_end
	s_waitcnt vmcnt(4)
	s_branch .Lcvtdn_loop
.Lcvtdn_end:
	s_waitcnt vmcnt(0)
.LBB0_1207:
	s_mov_b32 s0, -1
	s_waitcnt vmcnt(0)
	s_waitcnt lgkmcnt(0)
	s_barrier
	s_waitcnt vmcnt(1)
	v_mbcnt_lo_u32_b32 v0, s0, 0
	v_mbcnt_hi_u32_b32 v0, s0, v0
	v_or_b32_e32 v0, s1, v0
	s_nop 0
	v_cmp_eq_u32_e32 vcc, 0, v0
	s_and_saveexec_b64 s[0:1], vcc
	s_xor_b64 s[2:3], exec, s[0:1]
	s_cbranch_execz .LBB0_1260
	s_add_i32 s1, 0, 0x20000
	v_mov_b32_e32 v0, s1
	s_getreg_b32 s0, hwreg(HW_REG_XCC_ID, 0, 4)
	s_waitcnt vmcnt(0) expcnt(0) lgkmcnt(0)
	ds_read_b32 v2, v0
	v_mov_b32_e32 v0, s76
	ds_read_b32 v0, v0
	s_and_b32 s0, s0, 15
	s_waitcnt lgkmcnt(1)
	v_cmp_ne_u32_e32 vcc, 0, v2
	s_cbranch_vccnz .LBB0_1223
	s_add_u32 s6, s4, 0x27740200
	s_addc_u32 s7, s5, 0
	s_add_u32 s8, s4, 0x27740400
	s_addc_u32 s9, s5, 0
	s_add_u32 s10, s4, 0x27740500
	s_addc_u32 s11, s5, 0
	s_add_u32 s12, s4, 0x27740600
	s_addc_u32 s13, s5, 0
	s_add_u32 s14, s4, 0x27740700
	s_addc_u32 s15, s5, 0
	s_add_u32 s16, s4, 0x27740800
	s_addc_u32 s17, s5, 0
	s_add_u32 s18, s4, 0x27740900
	s_addc_u32 s19, s5, 0
	s_add_u32 s20, s4, 0x27740a00
	s_addc_u32 s21, s5, 0
	s_add_u32 s22, s4, 0x27740b00
	s_addc_u32 s23, s5, 0
	s_add_u32 s24, s4, 0x27740c00
	s_addc_u32 s25, s5, 0
	s_add_u32 s26, s4, 0x27740d00
	s_addc_u32 s27, s5, 0
	s_add_u32 s28, s4, 0x27740e00
	s_addc_u32 s29, s5, 0
	s_add_u32 s30, s4, 0x27740f00
	s_addc_u32 s31, s5, 0
	s_add_u32 s34, s4, 0x27741000
	s_addc_u32 s35, s5, 0
	s_add_u32 s36, s4, 0x27741100
	s_addc_u32 s37, s5, 0
	s_add_u32 s38, s4, 0x27741200
	s_addc_u32 s39, s5, 0
	s_add_u32 s40, s4, 0x27741300
	s_addc_u32 s41, s5, 0
	s_mov_b32 s48, 1
	s_branch .LBB0_1211
